# one static s_setprio 1 for the trailing half (waves 4-7) during each GEMM phase, reset at phase end; per-block flips stay removed
# baseline (speedup 1.0000x reference)
; #define PG8_STAGE(bufoff, gbase, voff) do { _Pragma("unroll") for (int _i = 0; _i < 2; ++_i) \
;         __builtin_amdgcn_global_load_lds((const unsigned*)((const char*)(gbase) + (voff)[_i]), (PG8_LAS unsigned*)(lds + (bufoff) + ldsw + _i * 8192), 16, 0, 0); } while (0)
; #define PG8_BAR __builtin_amdgcn_s_barrier()
; template <class Epi, class Sched, bool ALIGN_EPI = false, bool SP2 = false>
; __device__ __forceinline__ void gemm_phase(PG8_LAS unsigned char* lds, const Gemm g, const Sched& S, const Epi& E) {
;     int tid = threadIdx.x; asm volatile("" : "+v"(tid)); const int wid = __builtin_amdgcn_readfirstlane(tid >> 6), lane = tid & 63, wr = wid >> 2, wc = wid & 3, fr = lane & 15, fq = lane >> 4;
;     const int K = g.K, nt = K / BK;
;     unsigned voffA[2], voffB[2];
; #pragma unroll
;     for (int i = 0; i < 2; ++i) { int R, C; stage_rc(tid * 16 + i * 8192, R, C); const int Rb = Epi::PERM ? ((R & ~31) + perm32(R & 31)) : R;
;         voffA[i] = (unsigned)(R * K + C) * 2u; voffB[i] = (unsigned)(Rb * K + C) * 2u; }
;     const size_t kstep = (size_t)(BK * 2);
;     const size_t hstep = (size_t)HALF * K * 2;
;     const size_t tstep = 2 * hstep;
;     const unsigned ldsw = (unsigned)wid * 1024u;
;     const int aoff = lds_byte(wr * 64 + fr, fq * 8), boff = lds_byte(wc * 32 + fr, fq * 8);
;     ...
;     const char* cA = (const char*)g.A + (size_t)cur.pm * tstep; const char* cB = (const char*)g.Bt + (size_t)cur.pn * tstep;
;     S.a_ready(cur);
;     if constexpr (SP2) {
;         PG8_STAGE(PG8_SB(0, 0), cB, voffB); PG8_STAGE(PG8_SB(0, 1), cB + hstep, voffB); PG8_STAGE(PG8_SA(0, 0), cA, voffA); PG8_STAGE(PG8_SA(0, 1), cA + hstep, voffA);
;         if (wr == 1) PG8_BAR;
.Lxtail_p1body:
	v_readlane_b32 s22, v254, 2
	v_mov_b32_e32 v0, v232
	s_mov_b32 s38, 21
	s_mov_b32 s36, 21
	s_mov_b32 s26, 21
	s_mov_b32 s34, 21
	v_mov_b32_e32 v10, v232
	v_readlane_b32 s23, v254, 3
	s_andn2_b64 vcc, exec, s[22:23]
	v_readfirstlane_b32 s22, v10
	s_cbranch_vccnz .LBB0_145
	s_ashr_i32 s39, s38, 31
	s_lshl_b64 s[38:39], s[38:39], 3
	s_add_u32 s38, s0, s38
	s_addc_u32 s39, s1, s39
	s_load_dwordx2 s[38:39], s[38:39], 0x0
	v_lshlrev_b32_e32 v0, 4, v10
	v_add_u32_e32 v2, 0x2000, v0
	v_ashrrev_i32_e32 v3, 31, v2
	v_lshrrev_b32_e32 v3, 22, v3
	s_waitcnt lgkmcnt(0)
	s_add_u32 s55, s38, 0x18e00000
	s_addc_u32 s58, s39, 0
	s_ashr_i32 s37, s36, 31
	s_lshl_b64 s[36:37], s[36:37], 3
	s_add_u32 s36, s0, s36
	s_addc_u32 s37, s1, s37
	s_load_dwordx2 s[36:37], s[36:37], 0x0
	v_readlane_b32 s20, v255, 30
	v_add_u32_e32 v3, v2, v3
	s_mul_i32 s20, s20, 0xc80000
	v_ashrrev_i32_e32 v11, 10, v3
	s_lshl_b64 s[38:39], s[20:21], 1
	v_mul_i32_i24_e32 v3, 0x400, v11
	s_waitcnt lgkmcnt(0)
	s_add_u32 s20, s36, s38
	v_sub_u32_e32 v2, v2, v3
	s_addc_u32 s23, s37, s39
	v_lshrrev_b32_e32 v3, 4, v2
	s_add_u32 s20, s20, 0x200000
	v_bitop3_b32 v2, v3, v2, 32 bitop3:0x6c
	s_addc_u32 s59, s23, 0
	s_ashr_i32 s27, s26, 31
	v_ashrrev_i32_e32 v3, 31, v2
	s_lshl_b64 s[26:27], s[26:27], 3
	v_lshrrev_b32_e32 v3, 26, v3
	s_add_u32 s26, s0, s26
	v_add_u32_e32 v3, v2, v3
	v_lshlrev_b32_e32 v4, 3, v11
	s_addc_u32 s27, s1, s27
	s_ashr_i32 s35, s34, 31
	v_ashrrev_i32_e32 v12, 6, v3
	v_and_b32_e32 v4, -16, v4
	s_lshl_b64 s[34:35], s[34:35], 3
	v_add_u32_e32 v4, v12, v4
	s_add_u32 s36, s0, s34
	v_and_b32_e32 v5, 3, v12
	s_mov_b32 s34, 0xfffe0
	v_lshrrev_b32_e32 v6, 2, v4
	v_lshlrev_b32_e32 v7, 1, v4
	v_and_b32_e32 v3, 0xc0, v3
	v_and_or_b32 v5, v4, s34, v5
	v_and_b32_e32 v6, 4, v6
	v_and_b32_e32 v7, 24, v7
	v_sub_u32_e32 v2, v2, v3
	v_or3_b32 v5, v5, v6, v7
	v_lshlrev_b32_e32 v6, 5, v11
	v_ashrrev_i16_sdwa v2, v224, sext(v2) dst_sel:DWORD dst_unused:UNUSED_PAD src0_sel:DWORD src1_sel:BYTE_0
	v_and_b32_e32 v6, 32, v6
	v_bfe_i32 v13, v2, 0, 16
	v_add_lshl_u32 v2, v6, v13, 1
	v_lshl_add_u32 v130, v5, 12, v2
	v_lshl_add_u32 v132, v4, 12, v2
	v_bfe_i32 v2, v10, 27, 1
	v_lshrrev_b32_e32 v2, 22, v2
	v_add_u32_e32 v2, v0, v2
	v_and_b32_e32 v2, 0xfffffc00, v2
	v_sub_u32_e32 v0, v0, v2
	v_lshrrev_b32_e32 v2, 4, v0
	v_ashrrev_i32_e32 v3, 31, v10
	v_bitop3_b32 v0, v2, v0, 32 bitop3:0x6c
	v_lshrrev_b32_e32 v3, 26, v3
	v_ashrrev_i32_e32 v2, 31, v0
	v_add_u32_e32 v3, v10, v3
	v_lshrrev_b32_e32 v2, 26, v2
	v_ashrrev_i32_e32 v15, 6, v3
	v_add_u32_e32 v2, v0, v2
	v_lshlrev_b32_e32 v3, 3, v15
	v_ashrrev_i32_e32 v14, 6, v2
	v_and_b32_e32 v3, -16, v3
	v_add_u32_e32 v3, v14, v3
	v_and_b32_e32 v4, 3, v14
	v_lshrrev_b32_e32 v5, 2, v3
	v_lshlrev_b32_e32 v6, 1, v3
	v_and_b32_e32 v2, 0xc0, v2
	s_addc_u32 s37, s1, s35
	s_ashr_i32 s42, s22, 6
	v_and_or_b32 v4, v3, s34, v4
	v_and_b32_e32 v5, 4, v5
	v_and_b32_e32 v6, 24, v6
	v_sub_u32_e32 v0, v0, v2
	s_ashr_i32 s23, s22, 8
	s_lshl_b32 s74, s42, 10
	v_or3_b32 v4, v4, v5, v6
	v_lshlrev_b32_e32 v5, 5, v15
	v_ashrrev_i16_sdwa v0, v224, sext(v0) dst_sel:DWORD dst_unused:UNUSED_PAD src0_sel:DWORD src1_sel:BYTE_0
	v_readlane_b32 s34, v255, 16
	v_and_b32_e32 v5, 32, v5
	v_bfe_i32 v16, v0, 0, 16
	v_readlane_b32 s35, v255, 17
	s_add_u32 s34, s20, s34
	v_add_lshl_u32 v2, v5, v16, 1
	s_addc_u32 s35, s59, s35
	s_add_i32 s75, s74, 0
	v_lshl_add_u32 v0, v4, 12, v2
	s_add_i32 m0, s75, 0x10000
	v_lshl_add_u32 v134, v3, 12, v2
	global_load_lds_dwordx4 v0, s[34:35]
	s_add_i32 m0, s75, 0x12000
	s_add_u32 s38, s34, 0x80000
	global_load_lds_dwordx4 v130, s[34:35]
	s_addc_u32 s39, s35, 0
	s_add_i32 m0, s75, 0x14000
	v_mov_b32_e32 v131, v1
	global_load_lds_dwordx4 v0, s[38:39]
	s_add_i32 m0, s75, 0x16000
	v_mov_b32_e32 v135, v1
	global_load_lds_dwordx4 v130, s[38:39]
	v_readlane_b32 s38, v255, 33
	v_readlane_b32 s39, v255, 34
	s_add_u32 s48, s55, s38
	s_addc_u32 s49, s58, s39
	s_add_i32 s76, s75, 0x2000
	s_mov_b32 m0, s75
	s_add_u32 s38, s48, 0x80000
	global_load_lds_dwordx4 v134, s[48:49]
	s_mov_b32 m0, s76
	s_addc_u32 s39, s49, 0
	s_add_i32 s77, s75, 0x4000
	global_load_lds_dwordx4 v132, s[48:49]
	s_mov_b32 m0, s77
	s_add_i32 s78, s75, 0x6000
	global_load_lds_dwordx4 v134, s[38:39]
	s_mov_b32 m0, s78
	v_mov_b32_e32 v133, v1
	global_load_lds_dwordx4 v132, s[38:39]
	s_load_dwordx2 s[40:41], s[26:27], 0x0
	s_load_dwordx2 s[38:39], s[36:37], 0x0
	s_cmp_eq_u32 s23, 1
	v_lshl_add_u64 v[8:9], s[34:35], 0, v[0:1]
	v_lshl_add_u64 v[6:7], s[34:35], 0, v[130:131]
	v_lshl_add_u64 v[2:3], s[48:49], 0, v[134:135]
	s_cselect_b64 s[26:27], -1, 0
	s_cmp_lg_u32 s23, 1
	v_lshl_add_u64 v[4:5], s[48:49], 0, v[132:133]
	s_cbranch_scc1 .LBB0_132
	s_setprio 1
	s_barrier

; #define PG8_WAIT_V(n) asm volatile("s_waitcnt vmcnt(" #n ")" ::: "memory")
; #define PG8_BAR __builtin_amdgcn_s_barrier()
; template <class Epi, class Sched, bool ALIGN_EPI = false, bool SP2 = false>
; __device__ __forceinline__ void gemm_phase(PG8_LAS unsigned char* lds, const Gemm g, const Sched& S, const Epi& E) {
;     ...
;     PG8_WAIT_V(0);
;     if constexpr (!ALIGN_EPI) { if (wr == 0) PG8_BAR; }
;     PG8_BAR;
.LBB0_144:
	s_setprio 0
	s_load_dwordx2 s[58:59], s[0:1], 0xb0
	s_waitcnt vmcnt(0)
	v_readlane_b32 s74, v255, 47
	v_readlane_b32 s76, v255, 49
	v_readlane_b32 s78, v255, 51
	v_readlane_b32 s75, v255, 48
	v_readlane_b32 s77, v255, 50
	v_readlane_b32 s79, v255, 52
	v_readlane_b32 s55, v255, 53
	s_barrier
	s_cmp_eq_u32 s98, 0
	s_cbranch_scc1 .LBB0_145
	s_mov_b32 s98, 0
	v_readlane_b32 s80, v255, 57
	v_readlane_b32 s81, v255, 58
	v_readlane_b32 s82, v255, 59
	v_readlane_b32 s83, v255, 60
	v_readlane_b32 s84, v255, 61
	v_readlane_b32 s85, v255, 62
	s_nop 1
	v_writelane_b32 v255, s80, 15
	v_writelane_b32 v255, s81, 16
	v_writelane_b32 v255, s82, 17
	v_writelane_b32 v255, s83, 31
	v_writelane_b32 v255, s84, 33
	v_writelane_b32 v255, s85, 34
	v_mov_b32_e32 v226, 0x600
	v_mov_b32_e32 v227, 0
	v_mov_b32_e32 v228, 0x5ff
	v_mov_b32_e32 v229, 0
	s_waitcnt lgkmcnt(0)
	s_branch .Lxtail_p3_reentry

; #define PG8_STAGE(bufoff, gbase, voff) do { _Pragma("unroll") for (int _i = 0; _i < 2; ++_i) \
;         __builtin_amdgcn_global_load_lds((const unsigned*)((const char*)(gbase) + (voff)[_i]), (PG8_LAS unsigned*)(lds + (bufoff) + ldsw + _i * 8192), 16, 0, 0); } while (0)
; #define PG8_BAR __builtin_amdgcn_s_barrier()
; template <class Epi, class Sched, bool ALIGN_EPI = false, bool SP2 = false>
; __device__ __forceinline__ void gemm_phase(PG8_LAS unsigned char* lds, const Gemm g, const Sched& S, const Epi& E) {
;     int tid = threadIdx.x; asm volatile("" : "+v"(tid)); const int wid = __builtin_amdgcn_readfirstlane(tid >> 6), lane = tid & 63, wr = wid >> 2, wc = wid & 3, fr = lane & 15, fq = lane >> 4;
;     const int K = g.K, nt = K / BK;
;     unsigned voffA[2], voffB[2];
; #pragma unroll
;     for (int i = 0; i < 2; ++i) { int R, C; stage_rc(tid * 16 + i * 8192, R, C); const int Rb = Epi::PERM ? ((R & ~31) + perm32(R & 31)) : R;
;         voffA[i] = (unsigned)(R * K + C) * 2u; voffB[i] = (unsigned)(Rb * K + C) * 2u; }
;     const size_t kstep = (size_t)(BK * 2);
;     const size_t hstep = (size_t)HALF * K * 2;
;     const size_t tstep = 2 * hstep;
;     const unsigned ldsw = (unsigned)wid * 1024u;
;     const int aoff = lds_byte(wr * 64 + fr, fq * 8), boff = lds_byte(wc * 32 + fr, fq * 8);
;     ...
;     const char* cA = (const char*)g.A + (size_t)cur.pm * tstep; const char* cB = (const char*)g.Bt + (size_t)cur.pn * tstep;
;     S.a_ready(cur);
;     if constexpr (SP2) {
;         PG8_STAGE(PG8_SB(0, 0), cB, voffB); PG8_STAGE(PG8_SB(0, 1), cB + hstep, voffB); PG8_STAGE(PG8_SA(0, 0), cA, voffA); PG8_STAGE(PG8_SA(0, 1), cA + hstep, voffA);
;         if (wr == 1) PG8_BAR;
.LBB0_557:
	s_cmp_le_i32 s58, s20
	s_cselect_b64 s[4:5], -1, 0
	s_and_b64 s[22:23], s[4:5], s[26:27]
	s_andn2_b64 vcc, exec, s[22:23]
	v_readlane_b32 s22, v255, 11
	v_readlane_b32 s23, v255, 12
	s_nop 1
	v_cndmask_b32_e64 v0, 0, 1, s[22:23]
	v_cmp_ne_u32_e64 s[38:39], 1, v0
	s_cbranch_vccnz .LBB0_578
	v_mov_b32_e32 v0, v232
	s_mov_b32 s36, 21
	s_mov_b32 s34, 21
	s_mov_b32 s26, 21
	v_mov_b32_e32 v13, v232
	s_and_b64 vcc, exec, s[38:39]
	v_readfirstlane_b32 s22, v13
	s_cbranch_vccnz .LBB0_578
	s_ashr_i32 s37, s36, 31
	s_lshl_b64 s[36:37], s[36:37], 3
	s_add_u32 s36, s0, s36
	s_addc_u32 s37, s1, s37
	s_load_dwordx2 s[36:37], s[36:37], 0x0
	v_lshlrev_b32_e32 v0, 4, v13
	v_add_u32_e32 v2, 0x2000, v0
	v_ashrrev_i32_e32 v3, 31, v2
	v_lshrrev_b32_e32 v3, 22, v3
	v_add_u32_e32 v3, v2, v3
	s_waitcnt lgkmcnt(0)
	s_add_u32 s20, s36, 0x29600000
	v_ashrrev_i32_e32 v10, 10, v3
	s_addc_u32 s55, s37, 0
	s_ashr_i32 s35, s34, 31
	v_mul_i32_i24_e32 v3, 0x400, v10
	s_lshl_b64 s[34:35], s[34:35], 3
	v_sub_u32_e32 v2, v2, v3
	s_add_u32 s34, s0, s34
	v_lshrrev_b32_e32 v3, 4, v2
	s_addc_u32 s35, s1, s35
	v_bitop3_b32 v2, v3, v2, 32 bitop3:0x6c
	s_load_dwordx2 s[34:35], s[34:35], 0x0
	v_ashrrev_i32_e32 v3, 31, v2
	v_lshrrev_b32_e32 v3, 26, v3
	v_add_u32_e32 v3, v2, v3
	v_lshlrev_b32_e32 v4, 3, v10
	v_readlane_b32 s23, v255, 30
	v_ashrrev_i32_e32 v11, 6, v3
	v_and_b32_e32 v4, -16, v4
	s_lshl_b32 s23, s23, 23
	v_add_u32_e32 v4, v11, v4
	s_waitcnt lgkmcnt(0)
	s_add_u32 s23, s34, s23
	v_and_b32_e32 v5, 3, v11
	s_mov_b32 s34, 0xfffe0
	v_lshrrev_b32_e32 v6, 2, v4
	v_lshlrev_b32_e32 v7, 1, v4
	v_and_b32_e32 v3, 0xc0, v3
	v_and_or_b32 v5, v4, s34, v5
	v_and_b32_e32 v6, 4, v6
	v_and_b32_e32 v7, 24, v7
	v_sub_u32_e32 v2, v2, v3
	v_or3_b32 v5, v5, v6, v7
	v_lshlrev_b32_e32 v6, 5, v10
	v_ashrrev_i16_sdwa v2, v224, sext(v2) dst_sel:DWORD dst_unused:UNUSED_PAD src0_sel:DWORD src1_sel:BYTE_0
	v_and_b32_e32 v6, 32, v6
	v_bfe_i32 v12, v2, 0, 16
	v_add_lshl_u32 v2, v6, v12, 1
	v_lshl_add_u32 v130, v5, 12, v2
	v_lshl_add_u32 v132, v4, 12, v2
	v_bfe_i32 v2, v13, 27, 1
	v_lshrrev_b32_e32 v2, 22, v2
	v_add_u32_e32 v2, v0, v2
	v_and_b32_e32 v2, 0xfffffc00, v2
	v_sub_u32_e32 v0, v0, v2
	v_lshrrev_b32_e32 v2, 4, v0
	v_ashrrev_i32_e32 v3, 31, v13
	v_bitop3_b32 v0, v2, v0, 32 bitop3:0x6c
	v_lshrrev_b32_e32 v3, 26, v3
	v_ashrrev_i32_e32 v2, 31, v0
	v_add_u32_e32 v3, v13, v3
	s_addc_u32 s27, s35, 0
	v_lshrrev_b32_e32 v2, 26, v2
	v_ashrrev_i32_e32 v15, 6, v3
	s_add_u32 s58, s23, 0x6600000
	v_add_u32_e32 v2, v0, v2
	v_lshlrev_b32_e32 v3, 3, v15
	s_addc_u32 s59, s27, 0
	s_ashr_i32 s27, s26, 31
	v_ashrrev_i32_e32 v14, 6, v2
	v_and_b32_e32 v3, -16, v3
	s_lshl_b64 s[26:27], s[26:27], 3
	v_add_u32_e32 v3, v14, v3
	s_add_u32 s26, s0, s26
	v_and_b32_e32 v4, 3, v14
	v_lshrrev_b32_e32 v5, 2, v3
	v_lshlrev_b32_e32 v6, 1, v3
	v_and_b32_e32 v2, 0xc0, v2
	s_addc_u32 s27, s1, s27
	s_ashr_i32 s23, s22, 6
	v_and_or_b32 v4, v3, s34, v4
	v_and_b32_e32 v5, 4, v5
	v_and_b32_e32 v6, 24, v6
	v_sub_u32_e32 v0, v0, v2
	s_ashr_i32 s40, s22, 8
	s_lshl_b32 s74, s23, 10
	v_or3_b32 v4, v4, v5, v6
	v_lshlrev_b32_e32 v5, 5, v15
	v_ashrrev_i16_sdwa v0, v224, sext(v0) dst_sel:DWORD dst_unused:UNUSED_PAD src0_sel:DWORD src1_sel:BYTE_0
	v_readlane_b32 s34, v255, 19
	v_and_b32_e32 v5, 32, v5
	v_bfe_i32 v16, v0, 0, 16
	v_readlane_b32 s35, v255, 20
	s_add_u32 s34, s58, s34
	v_add_lshl_u32 v2, v5, v16, 1
	s_addc_u32 s35, s59, s35
	s_add_i32 s75, s74, 0
	v_lshl_add_u32 v0, v4, 12, v2
	s_add_i32 m0, s75, 0x10000
	v_lshl_add_u32 v134, v3, 12, v2
	global_load_lds_dwordx4 v0, s[34:35]
	s_add_i32 m0, s75, 0x12000
	s_add_u32 s36, s34, 0x80000
	global_load_lds_dwordx4 v130, s[34:35]
	s_addc_u32 s37, s35, 0
	s_add_i32 m0, s75, 0x14000
	v_mov_b32_e32 v131, v1
	global_load_lds_dwordx4 v0, s[36:37]
	s_add_i32 m0, s75, 0x16000
	v_mov_b32_e32 v135, v1
	global_load_lds_dwordx4 v130, s[36:37]
	v_readlane_b32 s36, v255, 37
	v_readlane_b32 s37, v255, 38
	s_add_u32 s48, s20, s36
	s_addc_u32 s49, s55, s37
	s_add_i32 s76, s75, 0x2000
	s_mov_b32 m0, s75
	s_add_u32 s36, s48, 0x80000
	global_load_lds_dwordx4 v134, s[48:49]
	s_mov_b32 m0, s76
	s_addc_u32 s37, s49, 0
	s_add_i32 s77, s75, 0x4000
	global_load_lds_dwordx4 v132, s[48:49]
	s_mov_b32 m0, s77
	s_add_i32 s78, s75, 0x6000
	global_load_lds_dwordx4 v134, s[36:37]
	s_mov_b32 m0, s78
	v_mov_b32_e32 v133, v1
	global_load_lds_dwordx4 v132, s[36:37]
	s_load_dwordx2 s[36:37], s[26:27], 0x0
	s_cmp_eq_u32 s40, 1
	v_lshl_add_u64 v[8:9], s[34:35], 0, v[0:1]
	v_lshl_add_u64 v[6:7], s[34:35], 0, v[130:131]
	v_lshl_add_u64 v[2:3], s[48:49], 0, v[134:135]
	s_cselect_b64 s[26:27], -1, 0
	s_cmp_lg_u32 s40, 1
	v_lshl_add_u64 v[4:5], s[48:49], 0, v[132:133]
	s_cbranch_scc1 .LBB0_561
	s_setprio 1
	s_barrier

; #define PG8_WAIT_V(n) asm volatile("s_waitcnt vmcnt(" #n ")" ::: "memory")
; #define PG8_BAR __builtin_amdgcn_s_barrier()
; template <class Epi, class Sched, bool ALIGN_EPI = false, bool SP2 = false>
; __device__ __forceinline__ void gemm_phase(PG8_LAS unsigned char* lds, const Gemm g, const Sched& S, const Epi& E) {
;     ...
;     PG8_WAIT_V(0);
;     if constexpr (!ALIGN_EPI) { if (wr == 0) PG8_BAR; }
;     PG8_BAR;
.LBB0_577:
	s_setprio 0
	s_load_dwordx2 s[58:59], s[0:1], 0xb0
	s_waitcnt vmcnt(0)
	v_readlane_b32 s74, v255, 47
	v_readlane_b32 s76, v255, 49
	v_readlane_b32 s78, v255, 51
	v_readlane_b32 s75, v255, 48
	v_readlane_b32 s77, v255, 50
	v_readlane_b32 s79, v255, 52
	v_readlane_b32 s55, v255, 53
	s_barrier

; #define PG8_STAGE(bufoff, gbase, voff) do { _Pragma("unroll") for (int _i = 0; _i < 2; ++_i) \
;         __builtin_amdgcn_global_load_lds((const unsigned*)((const char*)(gbase) + (voff)[_i]), (PG8_LAS unsigned*)(lds + (bufoff) + ldsw + _i * 8192), 16, 0, 0); } while (0)
; #define PG8_BAR __builtin_amdgcn_s_barrier()
; template <class Epi, class Sched, bool ALIGN_EPI = false, bool SP2 = false>
; __device__ __forceinline__ void gemm_phase(PG8_LAS unsigned char* lds, const Gemm g, const Sched& S, const Epi& E) {
;     int tid = threadIdx.x; asm volatile("" : "+v"(tid)); const int wid = __builtin_amdgcn_readfirstlane(tid >> 6), lane = tid & 63, wr = wid >> 2, wc = wid & 3, fr = lane & 15, fq = lane >> 4;
;     const int K = g.K, nt = K / BK;
;     unsigned voffA[2], voffB[2];
; #pragma unroll
;     for (int i = 0; i < 2; ++i) { int R, C; stage_rc(tid * 16 + i * 8192, R, C); const int Rb = Epi::PERM ? ((R & ~31) + perm32(R & 31)) : R;
;         voffA[i] = (unsigned)(R * K + C) * 2u; voffB[i] = (unsigned)(Rb * K + C) * 2u; }
;     const size_t kstep = (size_t)(BK * 2);
;     const size_t hstep = (size_t)HALF * K * 2;
;     const size_t tstep = 2 * hstep;
;     const unsigned ldsw = (unsigned)wid * 1024u;
;     const int aoff = lds_byte(wr * 64 + fr, fq * 8), boff = lds_byte(wc * 32 + fr, fq * 8);
;     ...
;     const char* cA = (const char*)g.A + (size_t)cur.pm * tstep; const char* cB = (const char*)g.Bt + (size_t)cur.pn * tstep;
;     S.a_ready(cur);
;     if constexpr (SP2) {
;         PG8_STAGE(PG8_SB(0, 0), cB, voffB); PG8_STAGE(PG8_SB(0, 1), cB + hstep, voffB); PG8_STAGE(PG8_SA(0, 0), cA, voffA); PG8_STAGE(PG8_SA(0, 1), cA + hstep, voffA);
;         if (wr == 1) PG8_BAR;
.LBB0_694:
	s_cmp_le_i32 s58, s20
	s_cselect_b64 s[4:5], -1, 0
	s_and_b64 s[22:23], s[4:5], s[26:27]
	s_andn2_b64 vcc, exec, s[22:23]
	s_cbranch_vccnz .LBB0_711
	v_readlane_b32 s22, v255, 13
	v_mov_b32_e32 v0, v232
	s_mov_b32 s40, 21
	s_mov_b32 s36, 21
	s_mov_b32 s26, 21
	s_mov_b32 s34, 21
	v_mov_b32_e32 v12, v232
	v_readlane_b32 s23, v255, 14
	s_andn2_b64 vcc, exec, s[22:23]
	v_readfirstlane_b32 s22, v12
	s_cbranch_vccnz .LBB0_711
	s_ashr_i32 s41, s40, 31
	s_lshl_b64 s[40:41], s[40:41], 3
	s_add_u32 s40, s0, s40
	s_addc_u32 s41, s1, s41
	s_load_dwordx2 s[40:41], s[40:41], 0x0
	v_lshlrev_b32_e32 v0, 4, v12
	v_add_u32_e32 v2, 0x2000, v0
	v_ashrrev_i32_e32 v3, 31, v2
	v_lshrrev_b32_e32 v3, 22, v3
	s_waitcnt lgkmcnt(0)
	s_add_u32 s55, s40, 0x18e00000
	s_addc_u32 s58, s41, 0
	s_ashr_i32 s37, s36, 31
	s_lshl_b64 s[36:37], s[36:37], 3
	s_add_u32 s36, s0, s36
	s_addc_u32 s37, s1, s37
	s_load_dwordx2 s[36:37], s[36:37], 0x0
	v_readlane_b32 s20, v255, 30
	v_add_u32_e32 v3, v2, v3
	s_mul_i32 s20, s20, 0x1600000
	v_ashrrev_i32_e32 v10, 10, v3
	s_lshl_b64 s[40:41], s[20:21], 1
	v_mul_i32_i24_e32 v3, 0x400, v10
	s_waitcnt lgkmcnt(0)
	s_add_u32 s20, s36, s40
	v_sub_u32_e32 v2, v2, v3
	s_addc_u32 s23, s37, s41
	v_lshrrev_b32_e32 v3, 4, v2
	s_add_u32 s20, s20, 0x8600000
	v_bitop3_b32 v2, v3, v2, 32 bitop3:0x6c
	s_addc_u32 s59, s23, 0
	s_ashr_i32 s27, s26, 31
	v_ashrrev_i32_e32 v3, 31, v2
	s_lshl_b64 s[26:27], s[26:27], 3
	v_lshrrev_b32_e32 v3, 26, v3
	s_add_u32 s26, s0, s26
	v_add_u32_e32 v3, v2, v3
	v_lshlrev_b32_e32 v4, 3, v10
	s_addc_u32 s27, s1, s27
	s_ashr_i32 s35, s34, 31
	v_ashrrev_i32_e32 v11, 6, v3
	v_and_b32_e32 v4, -16, v4
	s_lshl_b64 s[34:35], s[34:35], 3
	v_add_u32_e32 v4, v11, v4
	s_add_u32 s36, s0, s34
	v_and_b32_e32 v5, 3, v11
	s_mov_b32 s34, 0xfffe0
	v_lshrrev_b32_e32 v6, 2, v4
	v_lshlrev_b32_e32 v7, 1, v4
	v_and_b32_e32 v3, 0xc0, v3
	v_and_or_b32 v5, v4, s34, v5
	v_and_b32_e32 v6, 4, v6
	v_and_b32_e32 v7, 24, v7
	v_sub_u32_e32 v2, v2, v3
	v_or3_b32 v5, v5, v6, v7
	v_lshlrev_b32_e32 v6, 5, v10
	v_ashrrev_i16_sdwa v2, v224, sext(v2) dst_sel:DWORD dst_unused:UNUSED_PAD src0_sel:DWORD src1_sel:BYTE_0
	v_and_b32_e32 v6, 32, v6
	v_bfe_i32 v13, v2, 0, 16
	v_add_lshl_u32 v2, v6, v13, 1
	v_lshl_add_u32 v130, v5, 12, v2
	v_lshl_add_u32 v132, v4, 12, v2
	v_bfe_i32 v2, v12, 27, 1
	v_lshrrev_b32_e32 v2, 22, v2
	v_add_u32_e32 v2, v0, v2
	v_and_b32_e32 v2, 0xfffffc00, v2
	v_sub_u32_e32 v0, v0, v2
	v_lshrrev_b32_e32 v2, 4, v0
	v_ashrrev_i32_e32 v3, 31, v12
	v_bitop3_b32 v0, v2, v0, 32 bitop3:0x6c
	v_lshrrev_b32_e32 v3, 26, v3
	v_ashrrev_i32_e32 v2, 31, v0
	v_add_u32_e32 v3, v12, v3
	v_lshrrev_b32_e32 v2, 26, v2
	v_ashrrev_i32_e32 v15, 6, v3
	v_add_u32_e32 v2, v0, v2
	v_lshlrev_b32_e32 v3, 3, v15
	v_ashrrev_i32_e32 v14, 6, v2
	v_and_b32_e32 v3, -16, v3
	v_add_u32_e32 v3, v14, v3
	v_and_b32_e32 v4, 3, v14
	v_lshrrev_b32_e32 v5, 2, v3
	v_lshlrev_b32_e32 v6, 1, v3
	v_and_b32_e32 v2, 0xc0, v2
	s_addc_u32 s37, s1, s35
	s_ashr_i32 s23, s22, 6
	v_and_or_b32 v4, v3, s34, v4
	v_and_b32_e32 v5, 4, v5
	v_and_b32_e32 v6, 24, v6
	v_sub_u32_e32 v0, v0, v2
	s_ashr_i32 s44, s22, 8
	s_lshl_b32 s74, s23, 10
	v_or3_b32 v4, v4, v5, v6
	v_lshlrev_b32_e32 v5, 5, v15
	v_ashrrev_i16_sdwa v0, v224, sext(v0) dst_sel:DWORD dst_unused:UNUSED_PAD src0_sel:DWORD src1_sel:BYTE_0
	v_readlane_b32 s34, v255, 22
	v_and_b32_e32 v5, 32, v5
	v_bfe_i32 v16, v0, 0, 16
	v_readlane_b32 s35, v255, 23
	s_add_u32 s34, s20, s34
	v_add_lshl_u32 v2, v5, v16, 1
	s_addc_u32 s35, s59, s35
	s_add_i32 s75, s74, 0
	v_lshl_add_u32 v0, v4, 12, v2
	s_add_i32 m0, s75, 0x10000
	v_lshl_add_u32 v134, v3, 12, v2
	global_load_lds_dwordx4 v0, s[34:35]
	s_add_i32 m0, s75, 0x12000
	s_add_u32 s40, s34, 0x80000
	global_load_lds_dwordx4 v130, s[34:35]
	s_addc_u32 s41, s35, 0
	s_add_i32 m0, s75, 0x14000
	v_mov_b32_e32 v131, v1
	global_load_lds_dwordx4 v0, s[40:41]
	s_add_i32 m0, s75, 0x16000
	v_mov_b32_e32 v135, v1
	global_load_lds_dwordx4 v130, s[40:41]
	v_readlane_b32 s40, v255, 41
	v_readlane_b32 s41, v255, 42
	s_add_u32 s48, s55, s40
	s_addc_u32 s49, s58, s41
	s_add_i32 s76, s75, 0x2000
	s_mov_b32 m0, s75
	s_add_u32 s40, s48, 0x80000
	global_load_lds_dwordx4 v134, s[48:49]
	s_mov_b32 m0, s76
	s_addc_u32 s41, s49, 0
	s_add_i32 s77, s75, 0x4000
	global_load_lds_dwordx4 v132, s[48:49]
	s_mov_b32 m0, s77
	s_add_i32 s78, s75, 0x6000
	global_load_lds_dwordx4 v134, s[40:41]
	s_mov_b32 m0, s78
	v_mov_b32_e32 v133, v1
	global_load_lds_dwordx4 v132, s[40:41]
	s_load_dwordx2 s[42:43], s[26:27], 0x0
	s_load_dwordx2 s[40:41], s[36:37], 0x0
	s_cmp_eq_u32 s44, 1
	v_lshl_add_u64 v[8:9], s[34:35], 0, v[0:1]
	v_lshl_add_u64 v[6:7], s[34:35], 0, v[130:131]
	v_lshl_add_u64 v[2:3], s[48:49], 0, v[134:135]
	s_cselect_b64 s[26:27], -1, 0
	s_cmp_lg_u32 s44, 1
	v_lshl_add_u64 v[4:5], s[48:49], 0, v[132:133]
	s_cbranch_scc1 .LBB0_698
	s_setprio 1
	s_barrier

; #define PG8_STAGE(bufoff, gbase, voff) do { _Pragma("unroll") for (int _i = 0; _i < 2; ++_i) \
;         __builtin_amdgcn_global_load_lds((const unsigned*)((const char*)(gbase) + (voff)[_i]), (PG8_LAS unsigned*)(lds + (bufoff) + ldsw + _i * 8192), 16, 0, 0); } while (0)
; #define PG8_BAR __builtin_amdgcn_s_barrier()
; template <class Epi, class Sched, bool ALIGN_EPI = false, bool SP2 = false>
; __device__ __forceinline__ void gemm_phase(PG8_LAS unsigned char* lds, const Gemm g, const Sched& S, const Epi& E) {
;     int tid = threadIdx.x; asm volatile("" : "+v"(tid)); const int wid = __builtin_amdgcn_readfirstlane(tid >> 6), lane = tid & 63, wr = wid >> 2, wc = wid & 3, fr = lane & 15, fq = lane >> 4;
;     const int K = g.K, nt = K / BK;
;     unsigned voffA[2], voffB[2];
; #pragma unroll
;     for (int i = 0; i < 2; ++i) { int R, C; stage_rc(tid * 16 + i * 8192, R, C); const int Rb = Epi::PERM ? ((R & ~31) + perm32(R & 31)) : R;
;         voffA[i] = (unsigned)(R * K + C) * 2u; voffB[i] = (unsigned)(Rb * K + C) * 2u; }
;     const size_t kstep = (size_t)(BK * 2);
;     const size_t hstep = (size_t)HALF * K * 2;
;     const size_t tstep = 2 * hstep;
;     const unsigned ldsw = (unsigned)wid * 1024u;
;     const int aoff = lds_byte(wr * 64 + fr, fq * 8), boff = lds_byte(wc * 32 + fr, fq * 8);
;     ...
;     const char* cA = (const char*)g.A + (size_t)cur.pm * tstep; const char* cB = (const char*)g.Bt + (size_t)cur.pn * tstep;
;     S.a_ready(cur);
;     if constexpr (SP2) {
;         PG8_STAGE(PG8_SB(0, 0), cB, voffB); PG8_STAGE(PG8_SB(0, 1), cB + hstep, voffB); PG8_STAGE(PG8_SA(0, 0), cA, voffA); PG8_STAGE(PG8_SA(0, 1), cA + hstep, voffA);
;         if (wr == 1) PG8_BAR;
.LBB0_765:
	s_cmp_le_i32 s58, s20
	s_cselect_b64 s[4:5], -1, 0
	s_and_b64 s[22:23], s[4:5], s[26:27]
	s_andn2_b64 vcc, exec, s[22:23]
	s_cbranch_vccnz .LBB0_790
	v_mov_b32_e32 v0, v232
	s_mov_b32 s36, 21
	s_mov_b32 s34, 21
	s_mov_b32 s26, 21
	v_mov_b32_e32 v14, v232
	s_and_b64 vcc, exec, s[38:39]
	v_readfirstlane_b32 s22, v14
	s_cbranch_vccnz .LBB0_790
	s_ashr_i32 s37, s36, 31
	s_lshl_b64 s[36:37], s[36:37], 3
	s_add_u32 s36, s0, s36
	s_addc_u32 s37, s1, s37
	s_load_dwordx2 s[36:37], s[36:37], 0x0
	v_lshlrev_b32_e32 v0, 4, v14
	v_add_u32_e32 v2, 0x2000, v0
	v_ashrrev_i32_e32 v3, 31, v2
	v_lshrrev_b32_e32 v3, 22, v3
	v_add_u32_e32 v3, v2, v3
	s_waitcnt lgkmcnt(0)
	s_add_u32 s52, s36, 0x1ce00000
	v_ashrrev_i32_e32 v10, 10, v3
	s_addc_u32 s53, s37, 0
	s_ashr_i32 s35, s34, 31
	v_mul_i32_i24_e32 v3, 0x400, v10
	s_lshl_b64 s[34:35], s[34:35], 3
	v_sub_u32_e32 v2, v2, v3
	s_add_u32 s34, s0, s34
	v_lshrrev_b32_e32 v3, 4, v2
	s_addc_u32 s35, s1, s35
	v_bitop3_b32 v2, v3, v2, 32 bitop3:0x6c
	s_load_dwordx2 s[34:35], s[34:35], 0x0
	v_ashrrev_i32_e32 v3, 31, v2
	v_lshrrev_b32_e32 v3, 26, v3
	v_readlane_b32 s20, v255, 30
	v_add_u32_e32 v3, v2, v3
	v_lshlrev_b32_e32 v4, 3, v10
	s_mul_i32 s20, s20, 0xb00000
	v_ashrrev_i32_e32 v11, 6, v3
	v_and_b32_e32 v4, -16, v4
	s_lshl_b64 s[36:37], s[20:21], 1
	v_add_u32_e32 v4, v11, v4
	s_waitcnt lgkmcnt(0)
	s_add_u32 s20, s34, s36
	v_and_b32_e32 v5, 3, v11
	s_mov_b32 s34, 0x7fffe0
	v_lshrrev_b32_e32 v6, 2, v4
	v_lshlrev_b32_e32 v7, 1, v4
	v_and_b32_e32 v3, 0xc0, v3
	v_and_or_b32 v5, v4, s34, v5
	v_and_b32_e32 v6, 4, v6
	v_and_b32_e32 v7, 24, v7
	v_sub_u32_e32 v2, v2, v3
	v_or3_b32 v5, v5, v6, v7
	v_lshlrev_b32_e32 v6, 5, v10
	v_ashrrev_i16_sdwa v2, v224, sext(v2) dst_sel:DWORD dst_unused:UNUSED_PAD src0_sel:DWORD src1_sel:BYTE_0
	s_addc_u32 s23, s35, s37
	v_and_b32_e32 v12, 32, v6
	v_bfe_i32 v13, v2, 0, 16
	s_movk_i32 s35, 0x1600
	v_mul_u32_u24_e32 v5, 0x1600, v5
	v_add_u32_e32 v2, v12, v13
	v_mul_lo_u32 v3, v4, s35
	v_add_lshl_u32 v130, v5, v2, 1
	v_add_lshl_u32 v132, v2, v3, 1
	v_bfe_i32 v2, v14, 27, 1
	v_lshrrev_b32_e32 v2, 22, v2
	v_add_u32_e32 v2, v0, v2
	v_and_b32_e32 v2, 0xfffffc00, v2
	v_sub_u32_e32 v0, v0, v2
	v_lshrrev_b32_e32 v2, 4, v0
	v_ashrrev_i32_e32 v3, 31, v14
	v_bitop3_b32 v0, v2, v0, 32 bitop3:0x6c
	v_lshrrev_b32_e32 v3, 26, v3
	v_ashrrev_i32_e32 v2, 31, v0
	v_add_u32_e32 v3, v14, v3
	v_lshrrev_b32_e32 v2, 26, v2
	v_ashrrev_i32_e32 v16, 6, v3
	s_add_u32 s20, s20, 0x13600000
	v_add_u32_e32 v2, v0, v2
	v_lshlrev_b32_e32 v3, 3, v16
	s_addc_u32 s55, s23, 0
	s_ashr_i32 s27, s26, 31
	v_ashrrev_i32_e32 v15, 6, v2
	v_and_b32_e32 v3, -16, v3
	s_lshl_b64 s[26:27], s[26:27], 3
	v_add_u32_e32 v3, v15, v3
	s_add_u32 s26, s0, s26
	v_and_b32_e32 v4, 3, v15
	v_lshrrev_b32_e32 v5, 2, v3
	v_lshlrev_b32_e32 v6, 1, v3
	v_and_b32_e32 v2, 0xc0, v2
	s_addc_u32 s27, s1, s27
	s_ashr_i32 s23, s22, 6
	v_and_or_b32 v4, v3, s34, v4
	v_and_b32_e32 v5, 4, v5
	v_and_b32_e32 v6, 24, v6
	v_sub_u32_e32 v0, v0, v2
	v_mul_lo_u32 v3, v3, s35
	v_readlane_b32 s35, v255, 18
	s_ashr_i32 s38, s22, 8
	s_lshl_b32 s56, s23, 10
	v_or3_b32 v4, v4, v5, v6
	v_lshlrev_b32_e32 v5, 5, v16
	v_ashrrev_i16_sdwa v0, v224, sext(v0) dst_sel:DWORD dst_unused:UNUSED_PAD src0_sel:DWORD src1_sel:BYTE_0
	s_mul_i32 s34, s35, 0x2c0000
	v_and_b32_e32 v17, 32, v5
	v_bfe_i32 v18, v0, 0, 16
	s_add_u32 s34, s20, s34
	s_mul_hi_i32 s35, s35, 0x2c0000
	v_mul_u32_u24_e32 v4, 0x1600, v4
	v_add_u32_e32 v2, v17, v18
	s_addc_u32 s35, s55, s35
	s_add_i32 s57, s56, 0
	v_add_lshl_u32 v0, v4, v2, 1
	s_add_i32 m0, s57, 0x10000
	v_add_lshl_u32 v134, v2, v3, 1
	global_load_lds_dwordx4 v0, s[34:35]
	s_add_i32 m0, s57, 0x12000
	s_add_u32 s36, s34, 0x160000
	global_load_lds_dwordx4 v130, s[34:35]
	s_addc_u32 s37, s35, 0
	s_add_i32 m0, s57, 0x14000
	v_mov_b32_e32 v131, v1
	global_load_lds_dwordx4 v0, s[36:37]
	s_add_i32 m0, s57, 0x16000
	v_mov_b32_e32 v135, v1
	global_load_lds_dwordx4 v130, s[36:37]
	v_readlane_b32 s36, v255, 35
	s_mov_b32 s40, s36
	s_mul_i32 s36, s36, 0x2c0000
	s_add_u32 s46, s52, s36
	s_mul_hi_i32 s36, s40, 0x2c0000
	s_addc_u32 s47, s53, s36
	s_add_i32 s58, s57, 0x2000
	v_readlane_b32 s37, v255, 36
	s_mov_b32 m0, s57
	s_add_u32 s36, s46, 0x160000
	global_load_lds_dwordx4 v134, s[46:47]
	s_mov_b32 m0, s58
	s_addc_u32 s37, s47, 0
	s_add_i32 s59, s57, 0x4000
	global_load_lds_dwordx4 v132, s[46:47]
	s_mov_b32 m0, s59
	s_add_i32 s74, s57, 0x6000
	global_load_lds_dwordx4 v134, s[36:37]
	s_mov_b32 m0, s74
	v_mov_b32_e32 v133, v1
	global_load_lds_dwordx4 v132, s[36:37]
	s_load_dwordx2 s[36:37], s[26:27], 0x0
	s_cmp_eq_u32 s38, 1
	v_lshl_add_u64 v[8:9], s[34:35], 0, v[0:1]
	v_lshl_add_u64 v[6:7], s[34:35], 0, v[130:131]
	v_lshl_add_u64 v[2:3], s[46:47], 0, v[134:135]
	s_cselect_b64 s[26:27], -1, 0
	s_cmp_lg_u32 s38, 1
	v_lshl_add_u64 v[4:5], s[46:47], 0, v[132:133]
	s_cbranch_scc1 .LBB0_769
	s_setprio 1
	s_barrier
